# P2 work queue: next item index fetched ahead during the current item
# baseline (speedup 1.0000x reference)
.LBB0_696:
	s_or_b64 exec, exec, s[2:3]
	v_readlane_b32 s4, v255, 33
	v_readlane_b32 s5, v255, 34
	s_xor_b64 s[2:3], s[4:5], -1
	v_writelane_b32 v255, s2, 35
	s_lshl_b32 s58, s30, 4
	s_mov_b32 s10, s30
	v_writelane_b32 v255, s3, 36
	s_lshl_b64 s[2:3], s[58:59], 2
	s_add_u32 s2, s44, s2
	s_addc_u32 s3, s45, s3
	v_writelane_b32 v255, s2, 37
	s_mul_i32 s58, s30, 0x300
	s_mov_b32 s11, s59
	v_writelane_b32 v255, s3, 38
	s_and_b64 s[2:3], s[4:5], exec
	s_cselect_b32 s94, 64, 0
	s_cselect_b32 s53, 16, 0
	s_movk_i32 s3, 0x900
	s_cselect_b32 s2, 32, 0
	s_cselect_b32 s3, s3, 0x800
	s_or_b32 s4, s94, s53
	s_or_b32 s4, s4, s2
	s_bitset1_b32 s2, 8
	v_writelane_b32 v255, s2, 39
	s_lshl_b32 s2, s30, 2
	s_or_b32 s6, s4, s3
	v_writelane_b32 v255, s2, 40
	s_addk_i32 s6, 0x350
	s_lshl_b64 s[2:3], s[58:59], 2
	v_readlane_b32 s4, v255, 0
	s_add_u32 s4, s4, s2
	v_readlane_b32 s2, v255, 1
	s_addc_u32 s5, s2, s3
	v_writelane_b32 v255, s4, 41
	s_lshl_b64 s[2:3], s[10:11], 2
	v_mov_b32_e32 v228, 0x8f
	v_writelane_b32 v255, s5, 42
	v_readlane_b32 s4, v254, 16
	v_readlane_b32 s5, v254, 17
	s_add_u32 s4, s4, s2
	s_addc_u32 s5, s5, s3
	v_writelane_b32 v255, s4, 43
	s_barrier
	s_nop 0
	v_writelane_b32 v255, s5, 44
	s_nop 0
	v_readlane_b32 s4, v255, 23
	s_add_u32 s4, s4, s2
	v_readlane_b32 s2, v255, 24
	s_addc_u32 s5, s2, s3
	v_writelane_b32 v255, s4, 45
	s_nop 1
	v_writelane_b32 v255, s5, 46
	v_writelane_b32 v255, s10, 47
	s_lshl_b32 s58, s10, 6
	s_lshl_b64 s[2:3], s[58:59], 2
	v_writelane_b32 v255, s11, 48
	s_nop 0
	v_readlane_b32 s4, v255, 2
	s_add_u32 s34, s4, s2
	v_readlane_b32 s2, v255, 3
	s_addc_u32 s35, s2, s3
	v_cmp_eq_u32_e32 vcc, 0, v222
	s_and_saveexec_b64 s[2:3], vcc
	s_cbranch_execz .Lp2_q0
	v_readlane_b32 s10, v255, 37
	v_readlane_b32 s11, v255, 38
	v_mov_b32_e32 v230, 1
	s_nop 4
	global_atomic_add v229, v211, v230, s[10:11] offset:64 sc0
.Lp2_q0:
	s_or_b64 exec, exec, s[2:3]
	s_branch .LBB0_700

.LBB0_700:
	v_mov_b32_e32 v212, v222
	s_nop 0
	v_cmp_eq_u32_e32 vcc, 0, v212
	s_barrier
	s_and_saveexec_b64 s[2:3], vcc
	s_cbranch_execz .LBB0_704
	s_mov_b64 s[10:11], exec
	v_mbcnt_lo_u32_b32 v1, s10, 0
	v_mbcnt_hi_u32_b32 v1, s11, v1
	v_cmp_eq_u32_e32 vcc, 0, v1
	s_and_saveexec_b64 s[4:5], vcc
	s_cbranch_execz .LBB0_703
	s_bcnt1_i32_b64 s7, s[10:11]
	v_readlane_b32 s10, v255, 37
	v_mov_b32_e32 v230, s7
	v_readlane_b32 s11, v255, 38
	s_waitcnt vmcnt(0)
	v_mov_b32_e32 v2, v229
	s_nop 3
	global_atomic_add v229, v211, v230, s[10:11] offset:64 sc0
.LBB0_703:
	s_or_b64 exec, exec, s[4:5]
	v_readfirstlane_b32 s4, v2
	s_nop 1
	v_add_u32_e32 v1, s4, v1
	ds_write_b32 v214, v1
